# attention static priority moved to the younger half (waves 4-7) on the MFMA-shadow-interleaved loop
# speedup vs baseline: 1.0018x; 1.0018x over previous
; #define LAS __attribute__((address_space(3)))
; __device__ __forceinline__ int opaque_tid() { int t = threadIdx.x; asm volatile("" : "+v"(t)); return t; }
; __device__ __forceinline__ void attn_phase(char* lds, const Tens& T, int vcu, int G, bool nostore, bool with_meta) {
;     const int TOTAL = with_meta ? 512 + 16 : 512;
;     int L = vcu; if (L >= TOTAL) return;
;     int pass = 0;
;     Ref cur = make_ref(L, 0);
;     Seam S;
;     attn_prime(cur, T, lds, S);
; __global__ void __launch_bounds__(512, 2) fwd_megakernel(Params P) {
;     ...
;         if (s == 0 || s == 5 || s == 6) {
;             const int tid = opaque_tid(), lane = tid & 63, wave = __builtin_amdgcn_readfirstlane(tid >> 6);
;             const int vcu = (G % 8 == 0) ? (bx % 8) * (G / 8) + bx / 8 : bx;
;             if (s == 0) {
;             } else if (s == 5) {
;     ...
;                 mix_phase(P, l, vcu * 8 + wave, G * 8, lane, (LAS unsigned char*)lds);
;     ...
;             } else {
;     ...
;                 att::Tens T{ws}; att::attn_phase((char*)lds, T, vcu, G, ((DBL_MASK >> 6) & 1) && rep == 1, l == 0);
.LBB0_1455:
	s_and_b64 vcc, exec, s[2:3]
	s_cbranch_vccz .LBB0_1612
	v_mov_b32_e32 v129, v194
	s_andn2_b64 vcc, exec, s[26:27]
	v_readfirstlane_b32 s16, v129
	s_cbranch_vccnz .LBB0_1611
	v_readlane_b32 s0, v246, 17
	s_cmp_lg_u32 s0, 5
	s_mov_b64 s[0:1], -1
	s_cbranch_scc0 .LBB0_1565
	v_writelane_b32 v246, s16, 19
	v_writelane_b32 v246, s26, 21
	s_nop 1
	v_writelane_b32 v246, s27, 22
	s_nop 0
	v_readlane_b32 s0, v246, 13
	v_readlane_b32 s1, v246, 14
	s_and_b64 s[0:1], s[0:1], exec
	s_movk_i32 s0, 0x210
	s_cselect_b32 s26, 0x200, s0
	v_readlane_b32 s0, v247, 36
	s_cmp_ge_i32 s0, s26
	s_cbranch_scc1 .LBB0_1564
	v_readfirstlane_b32 s0, v194
	s_nop 3
	s_cmpk_lt_u32 s0, 0x100
	s_cbranch_scc1 .La_prio_done
	s_setprio 2
